# S2 + last-step peel (no dropped-tile S/exp/DMA work) + XCD-local release for GEMM->GEMM barriers
# speedup vs baseline: 1.0105x; 1.0105x over previous
.LBB0_291:
	s_cmp_eq_u32 s76, 60
	s_cbranch_scc1 .Llast_odd
	ds_read_b128 v[174:177], v202
	ds_read_b128 v[170:173], v202 offset:8192
	ds_read_b128 v[166:169], v204
	ds_read_b128 v[162:165], v204 offset:8192
	ds_read_b128 v[158:161], v205
	ds_read_b128 v[154:157], v205 offset:8192
	ds_read_b128 v[150:153], v206
	ds_read_b128 v[146:149], v206 offset:8192
	s_addk_i32 s78, 0x80
	s_and_b32 s15, s78, 0xf80
	s_or_b32 s0, s15, 63
	s_cmp_gt_i32 s0, s74
	s_cselect_b64 s[0:1], -1, 0
	s_cmp_lt_i32 s15, s75
	s_cselect_b64 s[40:41], -1, 0
	s_and_b64 s[0:1], s[0:1], s[40:41]
	s_andn2_b64 vcc, exec, s[0:1]
	s_mov_b64 s[0:1], -1
	s_cbranch_vccz .LBB0_293
	s_waitcnt lgkmcnt(7)
	v_mfma_f32_32x32x16_bf16 v[66:81], v[174:177], v[130:133], 0
	s_mov_b64 s[0:1], 0
	s_waitcnt lgkmcnt(6)
	v_mfma_f32_32x32x16_bf16 v[82:97], v[170:173], v[130:133], 0

.Llast_odd:
	v_add_f32_e32 v174, v114, v115
	v_add_f32_e32 v175, v116, v117
	v_add_f32_e32 v176, v118, v119
	v_add_f32_e32 v177, v120, v121
	v_add_f32_e32 v174, v174, v122
	v_add_f32_e32 v175, v175, v123
	v_add_f32_e32 v176, v176, v124
	v_add_f32_e32 v177, v177, v125
	v_add_f32_e32 v174, v174, v126
	v_add_f32_e32 v175, v175, v127
	v_add_f32_e32 v176, v176, v128
	v_add_f32_e32 v177, v177, v129
	v_add_f32_e32 v174, v174, v98
	v_add_f32_e32 v175, v175, v99
	v_add_f32_e32 v176, v176, v100
	v_add_f32_e32 v177, v177, v101
	v_add_f32_e32 v174, v174, v102
	v_add_f32_e32 v175, v175, v103
	v_add_f32_e32 v176, v176, v104
	v_add_f32_e32 v177, v177, v105
	v_add_f32_e32 v174, v174, v106
	v_add_f32_e32 v175, v175, v107
	v_add_f32_e32 v176, v176, v108
	v_add_f32_e32 v177, v177, v109
	v_add_f32_e32 v174, v174, v110
	v_add_f32_e32 v175, v175, v111
	v_add_f32_e32 v176, v176, v112
	v_add_f32_e32 v177, v177, v113
	v_add_f32_e32 v174, v174, v175
	v_add_f32_e32 v176, v176, v177
	v_cvt_pk_bf16_f32 v113, v112, v113
	v_cvt_pk_bf16_f32 v112, v110, v111
	v_cvt_pk_bf16_f32 v111, v108, v109
	v_cvt_pk_bf16_f32 v110, v106, v107
	v_add_f32_e32 v174, v174, v176
	v_cvt_pk_bf16_f32 v109, v104, v105
	v_cvt_pk_bf16_f32 v108, v102, v103
	v_cvt_pk_bf16_f32 v107, v100, v101
	v_cvt_pk_bf16_f32 v106, v98, v99
	v_cvt_pk_bf16_f32 v98, v114, v115
	v_cvt_pk_bf16_f32 v99, v116, v117
	v_cvt_pk_bf16_f32 v100, v118, v119
	v_cvt_pk_bf16_f32 v101, v120, v121
	v_cvt_pk_bf16_f32 v102, v122, v123
	v_cvt_pk_bf16_f32 v103, v124, v125
	v_cvt_pk_bf16_f32 v104, v126, v127
	v_cvt_pk_bf16_f32 v105, v128, v129
	v_add_f32_e32 v213, v174, v0
	ds_read_b128 v[114:117], v208 offset:49152
	ds_read_b128 v[118:121], v208 offset:53248
	ds_read_b128 v[122:125], v208 offset:57344
	ds_read_b128 v[126:129], v208 offset:61440
	ds_read_b128 v[150:153], v209 offset:53248
	ds_read_b128 v[146:149], v209 offset:49152
	ds_read_b128 v[154:157], v209 offset:57344
	ds_read_b128 v[158:161], v209 offset:61440
	s_waitcnt lgkmcnt(0)
	v_mfma_f32_32x32x16_bf16 v[50:65], v[98:101], v[114:117], v[50:65]
	ds_read_b128 v[114:117], v210 offset:53248
	v_mfma_f32_32x32x16_bf16 v[34:49], v[98:101], v[118:121], v[34:49]
	ds_read_b128 v[118:121], v210 offset:57344
	v_mfma_f32_32x32x16_bf16 v[18:33], v[98:101], v[122:125], v[18:33]
	ds_read_b128 v[122:125], v210 offset:61440
	v_mfma_f32_32x32x16_bf16 v[2:17], v[98:101], v[126:129], v[2:17]
	ds_read_b128 v[98:101], v210 offset:49152
	v_mfma_f32_32x32x16_bf16 v[50:65], v[102:105], v[146:149], v[50:65]
	ds_read_b128 v[126:129], v212 offset:53248
	v_mfma_f32_32x32x16_bf16 v[34:49], v[102:105], v[150:153], v[34:49]
	ds_read_b128 v[146:149], v212 offset:57344
	v_mfma_f32_32x32x16_bf16 v[18:33], v[102:105], v[154:157], v[18:33]
	ds_read_b128 v[150:153], v212 offset:61440
	v_mfma_f32_32x32x16_bf16 v[2:17], v[102:105], v[158:161], v[2:17]
	ds_read_b128 v[102:105], v212 offset:49152
	s_waitcnt lgkmcnt(0)
	v_mfma_f32_32x32x16_bf16 v[50:65], v[106:109], v[98:101], v[50:65]
	v_mfma_f32_32x32x16_bf16 v[34:49], v[106:109], v[114:117], v[34:49]
	v_mfma_f32_32x32x16_bf16 v[18:33], v[106:109], v[118:121], v[18:33]
	v_mfma_f32_32x32x16_bf16 v[2:17], v[106:109], v[122:125], v[2:17]
	v_mfma_f32_32x32x16_bf16 v[50:65], v[110:113], v[102:105], v[50:65]
	v_mfma_f32_32x32x16_bf16 v[34:49], v[110:113], v[126:129], v[34:49]
	v_mfma_f32_32x32x16_bf16 v[18:33], v[110:113], v[146:149], v[18:33]
	v_mfma_f32_32x32x16_bf16 v[2:17], v[110:113], v[150:153], v[2:17]
	s_barrier
	s_waitcnt vmcnt(0)
	s_branch .LBB0_295
